# baseline (speedup 1.0000x reference)
; __device__ __forceinline__ unsigned cvt_pk_bf16(float lo, float hi) { f32x2_t v = {lo, hi}; bf16x2_t r = __builtin_convertvector(v, bf16x2_t); return __builtin_bit_cast(unsigned, r); }
; __device__ __forceinline__ void phase0(CParams* pp, LAS unsigned char* lds, int G, int bid, int wave, int lane, int tid) {
;     ...
;     for (int row = gw; row < S; row += NGW) {
;         const f32x4* xr = (const f32x4*)(X + (size_t)row * DM) + lane; u32x2* o8 = (u32x2*)(XB + (size_t)row * DM) + lane;
;         float sq = 0.f;
; #pragma unroll
;         for (int j = 0; j < 8; ++j) { const f32x4 v = xr[64 * j]; sq += (v[0] * v[0] + v[1] * v[1]) + (v[2] * v[2] + v[3] * v[3]);
;             u32x2 w; w.x = pg8::cvt_pk_bf16(v[0], v[1]); w.y = pg8::cvt_pk_bf16(v[2], v[3]); o8[64 * j] = w; }
;         sq = wave_sum(sq);
;         if (lane < 32) ssq[(size_t)row * 32 + lane] = lane == 0 ? sq : 0.f;
.LBB0_31:
	s_waitcnt lgkmcnt(0)
	v_add_co_u32_e32 v10, vcc, 0xfffff000, v6
	v_lshl_add_u64 v[20:21], s[22:23], 0, v[4:5]
	s_nop 0
	v_addc_co_u32_e32 v11, vcc, -1, v7, vcc
	v_add_co_u32_e32 v48, vcc, s3, v20
	s_nop 0
	v_addc_co_u32_e32 v49, vcc, 0, v21, vcc
	global_load_dwordx4 v[16:19], v[10:11], off offset:-3072
	global_load_dwordx4 v[20:23], v[10:11], off offset:-2048
	global_load_dwordx4 v[24:27], v[10:11], off offset:-1024
	global_load_dwordx4 v[28:31], v[6:7], off offset:-4096
	global_load_dwordx4 v[32:35], v[6:7], off offset:-3072
	global_load_dwordx4 v[36:39], v[6:7], off offset:-2048
	global_load_dwordx4 v[40:43], v[6:7], off offset:-1024
	global_load_dwordx4 v[44:47], v[6:7], off
	s_waitcnt vmcnt(0)
	v_cvt_pk_bf16_f32 v10, v16, v17
	v_cvt_pk_bf16_f32 v11, v18, v19
	global_store_dwordx2 v[48:49], v[10:11], off
	s_nop 1
	v_mul_f32_e32 v1, v17, v17
	v_fmac_f32_e32 v1, v16, v16
	v_mul_f32_e32 v10, v19, v19
	v_fmac_f32_e32 v10, v18, v18
	v_add_f32_e32 v1, v1, v10
	v_cvt_pk_bf16_f32 v10, v20, v21
	v_cvt_pk_bf16_f32 v11, v22, v23
	global_store_dwordx2 v[48:49], v[10:11], off offset:512
	s_nop 1
	v_mul_f32_e32 v10, v21, v21
	v_mul_f32_e32 v11, v23, v23
	v_fmac_f32_e32 v10, v20, v20
	v_fmac_f32_e32 v11, v22, v22
	v_add_f32_e32 v10, v10, v11
	v_add_f32_e32 v1, v1, v10
	v_cvt_pk_bf16_f32 v10, v24, v25
	v_cvt_pk_bf16_f32 v11, v26, v27
	global_store_dwordx2 v[48:49], v[10:11], off offset:1024
	s_nop 1
	v_mul_f32_e32 v10, v25, v25
	v_mul_f32_e32 v11, v27, v27
	v_fmac_f32_e32 v10, v24, v24
	v_fmac_f32_e32 v11, v26, v26
	v_add_f32_e32 v10, v10, v11
	v_add_f32_e32 v1, v1, v10
	v_cvt_pk_bf16_f32 v10, v28, v29
	v_cvt_pk_bf16_f32 v11, v30, v31
	global_store_dwordx2 v[48:49], v[10:11], off offset:1536
	s_nop 1
	v_mul_f32_e32 v10, v29, v29
	v_mul_f32_e32 v11, v31, v31
	v_fmac_f32_e32 v10, v28, v28
	v_fmac_f32_e32 v11, v30, v30
	v_add_f32_e32 v10, v10, v11
	v_add_f32_e32 v1, v1, v10
	v_cvt_pk_bf16_f32 v10, v32, v33
	v_cvt_pk_bf16_f32 v11, v34, v35
	global_store_dwordx2 v[48:49], v[10:11], off offset:2048
	s_nop 1
	v_mul_f32_e32 v10, v33, v33
	v_mul_f32_e32 v11, v35, v35
	v_fmac_f32_e32 v10, v32, v32
	v_fmac_f32_e32 v11, v34, v34
	v_add_f32_e32 v10, v10, v11
	v_add_f32_e32 v1, v1, v10
	v_cvt_pk_bf16_f32 v10, v36, v37
	v_cvt_pk_bf16_f32 v11, v38, v39
	global_store_dwordx2 v[48:49], v[10:11], off offset:2560
	s_nop 1
	v_mul_f32_e32 v10, v37, v37
	v_mul_f32_e32 v11, v39, v39
	v_fmac_f32_e32 v10, v36, v36
	v_fmac_f32_e32 v11, v38, v38
	v_add_f32_e32 v10, v10, v11
	v_add_f32_e32 v1, v1, v10
	v_cvt_pk_bf16_f32 v10, v40, v41
	v_cvt_pk_bf16_f32 v11, v42, v43
	global_store_dwordx2 v[48:49], v[10:11], off offset:3072
	s_nop 1
	v_mul_f32_e32 v10, v41, v41
	v_mul_f32_e32 v11, v43, v43
	v_fmac_f32_e32 v10, v40, v40
	v_fmac_f32_e32 v11, v42, v42
	v_add_f32_e32 v10, v10, v11
	v_add_f32_e32 v1, v1, v10
	v_cvt_pk_bf16_f32 v10, v44, v45
	v_cvt_pk_bf16_f32 v11, v46, v47
	global_store_dwordx2 v[48:49], v[10:11], off offset:3584
	s_nop 1
	v_mul_f32_e32 v10, v45, v45
	v_mul_f32_e32 v11, v47, v47
	v_fmac_f32_e32 v10, v44, v44
	v_fmac_f32_e32 v11, v46, v46
	v_add_f32_e32 v10, v10, v11
	v_add_f32_e32 v1, v1, v10
	ds_bpermute_b32 v10, v8, v1
	s_waitcnt lgkmcnt(0)
	v_add_f32_e32 v1, v1, v10
	ds_bpermute_b32 v10, v9, v1
	s_waitcnt lgkmcnt(0)
	v_add_f32_e32 v1, v1, v10
	ds_bpermute_b32 v10, v12, v1
	s_waitcnt lgkmcnt(0)
	v_add_f32_e32 v1, v1, v10
	ds_bpermute_b32 v10, v13, v1
	s_waitcnt lgkmcnt(0)
	v_add_f32_e32 v1, v1, v10
	ds_bpermute_b32 v10, v14, v1
	s_waitcnt lgkmcnt(0)
	v_add_f32_e32 v1, v1, v10
	ds_bpermute_b32 v10, v15, v1
	s_and_saveexec_b64 s[24:25], s[4:5]
	s_cbranch_execz .LBB0_30
	s_waitcnt lgkmcnt(0)
	v_add_f32_e32 v1, v1, v10
	v_cndmask_b32_e64 v1, 0, v1, s[6:7]
	v_lshl_add_u64 v[10:11], s[22:23], 0, v[2:3]
	global_store_dword v[10:11], v1, off
	s_branch .LBB0_30
